# v87 plus butterfly wave reductions of the LN statistics done with DPP / permlane swaps instead of ds_bpermute, in the F loop and the J layer-1 loop
# baseline (speedup 1.0000x reference)
.LBB0_1705:
	s_mov_b64 s[10:11], s[0:1]
	v_mov_b32_e32 v2, v0
	s_mov_b64 s[22:23], s[44:45]
	v_mov_b32_e32 v1, v232
	s_mov_b64 s[18:19], s[46:47]
	s_add_i32 s9, s60, s8
	v_lshlrev_b32_e32 v2, 2, v1
	v_ashrrev_i32_e32 v3, 31, v2
	v_lshlrev_b64 v[4:5], 1, v[2:3]
	v_lshl_add_u64 v[8:9], s[18:19], 0, v[4:5]
	v_lshl_add_u64 v[8:9], v[8:9], 0, s[16:17]
	global_load_dwordx2 v[56:57], v[8:9], off offset:-3584
	global_load_dwordx2 v[62:63], v[8:9], off offset:-3072
	global_load_dwordx2 v[66:67], v[8:9], off offset:-2560
	global_load_dwordx2 v[10:11], v[8:9], off offset:-2048
	s_cmpk_lt_i32 s9, 0x2000
	s_cselect_b32 s24, s9, s8
	s_ashr_i32 s25, s24, 31
	s_lshl_b64 s[20:21], s[24:25], 12
	s_add_u32 s18, s18, s20
	s_addc_u32 s19, s19, s21
	v_lshl_add_u64 v[4:5], s[18:19], 0, v[4:5]
	v_lshl_add_u64 v[224:225], v[4:5], 0, s[54:55]
	global_load_dwordx2 v[92:93], v[8:9], off offset:-1536
	global_load_dwordx2 v[98:99], v[8:9], off offset:-1024
	global_load_dwordx2 v[100:101], v[8:9], off offset:-512
	global_load_dwordx2 v[108:109], v[8:9], off
	global_load_dwordx2 v[110:111], v[224:225], off
	global_load_dwordx2 v[118:119], v[224:225], off offset:512
	global_load_dwordx2 v[120:121], v[224:225], off offset:1024
	global_load_dwordx2 v[122:123], v[224:225], off offset:1536
	global_load_dwordx2 v[144:145], v[224:225], off offset:2048
	global_load_dwordx2 v[146:147], v[224:225], off offset:2560
	global_load_dwordx2 v[152:153], v[224:225], off offset:3072
	global_load_dwordx2 v[154:155], v[224:225], off offset:3584
	v_and_b32_e32 v7, 64, v249
	v_add_u32_e32 v12, 64, v7
	v_xor_b32_e32 v7, 1, v249
	s_waitcnt vmcnt(3)
	v_lshlrev_b32_e32 v68, 16, v56
	s_waitcnt vmcnt(2)
	v_lshlrev_b32_e32 v69, 16, v62
	v_and_b32_e32 v71, 0xffff0000, v62
	s_waitcnt vmcnt(0)
	v_lshlrev_b32_e32 v58, 16, v10
	v_and_b32_e32 v59, 0xffff0000, v10
	v_lshlrev_b32_e32 v60, 16, v11
	v_and_b32_e32 v61, 0xffff0000, v11
	s_nop 1
	v_mov_b64_e32 v[10:11], v[92:93]
	v_and_b32_e32 v70, 0xffff0000, v56
	v_lshlrev_b32_e32 v65, 16, v63
	v_lshlrev_b32_e32 v64, 16, v57
	v_and_b32_e32 v75, 0xffff0000, v63
	v_and_b32_e32 v74, 0xffff0000, v57
	v_pk_add_f32 v[56:57], v[64:65], v[74:75]
	v_lshlrev_b32_e32 v63, 16, v67
	v_lshlrev_b32_e32 v62, 16, v66
	v_and_b32_e32 v73, 0xffff0000, v67
	v_and_b32_e32 v72, 0xffff0000, v66
	v_add_f32_e32 v54, v58, v59
	v_add_f32_e32 v52, v60, v61
	s_nop 0
	v_lshlrev_b32_e32 v51, 16, v10
	v_and_b32_e32 v49, 0xffff0000, v10
	v_lshlrev_b32_e32 v55, 16, v11
	v_and_b32_e32 v53, 0xffff0000, v11
	s_nop 1
	v_mov_b64_e32 v[76:77], v[98:99]
	s_nop 1
	v_mov_b64_e32 v[10:11], v[100:101]
	s_nop 0
	v_lshlrev_b32_e32 v46, 16, v11
	s_nop 1
	v_mov_b64_e32 v[8:9], v[108:109]
	v_and_b32_e32 v47, 0xffff0000, v11
	v_lshlrev_b32_e32 v40, 16, v10
	v_and_b32_e32 v41, 0xffff0000, v10
	v_add_f32_e32 v44, v40, v41
	v_add_f32_e32 v42, v46, v47
	s_nop 0
	v_lshlrev_b32_e32 v38, 16, v8
	v_and_b32_e32 v39, 0xffff0000, v8
	v_lshlrev_b32_e32 v45, 16, v9
	v_and_b32_e32 v43, 0xffff0000, v9
	v_lshl_add_u64 v[8:9], v[4:5], 0, s[54:55]
	v_add_co_u32_e32 v4, vcc, s27, v4
	s_nop 1
	v_addc_co_u32_e32 v5, vcc, 0, v5, vcc
	s_nop 1
	v_mov_b64_e32 v[34:35], v[110:111]
	s_nop 1
	v_mov_b64_e32 v[36:37], v[118:119]
	s_nop 1
	v_mov_b64_e32 v[32:33], v[120:121]
	s_nop 0
	s_nop 1
	v_mov_b64_e32 v[4:5], v[122:123]
	v_cmp_lt_i32_e32 vcc, v7, v12
	s_nop 0
	v_lshlrev_b32_e32 v26, 16, v4
	v_and_b32_e32 v27, 0xffff0000, v4
	v_lshlrev_b32_e32 v28, 16, v5
	v_and_b32_e32 v29, 0xffff0000, v5
	s_nop 1
	v_mov_b64_e32 v[4:5], v[144:145]
	v_cndmask_b32_e32 v7, v249, v7, vcc
	v_lshlrev_b32_e32 v7, 2, v7
	v_add_f32_e32 v24, v26, v27
	s_nop 0
	v_lshlrev_b32_e32 v21, 16, v4
	v_and_b32_e32 v19, 0xffff0000, v4
	v_lshlrev_b32_e32 v25, 16, v5
	v_and_b32_e32 v23, 0xffff0000, v5
	s_nop 1
	v_mov_b64_e32 v[30:31], v[146:147]
	s_nop 1
	v_mov_b64_e32 v[4:5], v[152:153]
	s_load_dwordx4 s[28:31], s[10:11], 0xb0
	s_waitcnt lgkmcnt(0)
	s_add_u32 s20, s28, 0x2000
	s_addc_u32 s21, s29, 0
	s_add_u32 s18, s30, 0x2000
	s_addc_u32 s19, s31, 0
	s_nop 0
	v_lshlrev_b32_e32 v14, 16, v4
	v_and_b32_e32 v15, 0xffff0000, v4
	v_lshlrev_b32_e32 v16, 16, v5
	v_and_b32_e32 v17, 0xffff0000, v5
	s_nop 1
	v_mov_b64_e32 v[4:5], v[154:155]
	s_nop 0
	v_lshlrev_b32_e32 v8, 16, v4
	v_and_b32_e32 v9, 0xffff0000, v4
	v_lshlrev_b32_e32 v13, 16, v5
	v_and_b32_e32 v11, 0xffff0000, v5
	v_pk_add_f32 v[4:5], v[68:69], v[70:71]
	s_nop 0
	v_pk_add_f32 v[4:5], v[4:5], v[56:57]
	v_pk_add_f32 v[56:57], v[54:55], v[52:53]
	v_add_f32_e32 v4, 0, v4
	v_add_f32_e32 v50, v4, v5
	v_pk_add_f32 v[4:5], v[62:63], v[72:73]
	s_nop 0
	v_pk_add_f32 v[4:5], v[4:5], v[4:5] op_sel:[0,1] op_sel_hi:[1,0]
	s_nop 0
	v_mov_b32_e32 v5, v49
	v_pk_add_f32 v[4:5], v[50:51], v[4:5]
	s_nop 0
	v_pk_add_f32 v[66:67], v[4:5], v[56:57]
	v_lshlrev_b32_e32 v57, 16, v77
	v_lshlrev_b32_e32 v56, 16, v76
	v_and_b32_e32 v5, 0xffff0000, v77
	v_and_b32_e32 v4, 0xffff0000, v76
	v_pk_add_f32 v[76:77], v[56:57], v[4:5]
	v_pk_add_f32 v[66:67], v[66:67], v[66:67] op_sel:[0,1] op_sel_hi:[1,0]
	v_pk_add_f32 v[76:77], v[76:77], v[76:77] op_sel:[0,1] op_sel_hi:[1,0]
	v_mov_b32_e32 v67, v38
	v_mov_b32_e32 v77, v39
	v_pk_add_f32 v[66:67], v[66:67], v[76:77]
	v_pk_add_f32 v[76:77], v[44:45], v[42:43]
	v_lshlrev_b32_e32 v44, 16, v35
	v_pk_add_f32 v[66:67], v[66:67], v[76:77]
	s_nop 0
	v_add_f32_e32 v10, v66, v67
	s_nop 1
	v_mov_b32_dpp v18, v10 quad_perm:[1,0,3,2] row_mask:0xf bank_mask:0xf
	s_waitcnt lgkmcnt(0)
	v_add_f32_e32 v10, v10, v18
	v_xor_b32_e32 v18, 2, v249
	v_cmp_lt_i32_e32 vcc, v18, v12
	s_nop 1
	v_cndmask_b32_e32 v18, v249, v18, vcc
	v_lshlrev_b32_e32 v18, 2, v18
	s_nop 1
	v_mov_b32_dpp v20, v10 quad_perm:[2,3,0,1] row_mask:0xf bank_mask:0xf
	s_waitcnt lgkmcnt(0)
	v_add_f32_e32 v10, v10, v20
	v_xor_b32_e32 v20, 4, v249
	v_cmp_lt_i32_e32 vcc, v20, v12
	s_nop 1
	v_cndmask_b32_e32 v20, v249, v20, vcc
	v_lshlrev_b32_e32 v50, 2, v20
	s_nop 1
	v_mov_b32_dpp v20, v10 row_half_mirror row_mask:0xf bank_mask:0xf
	s_waitcnt lgkmcnt(0)
	v_add_f32_e32 v10, v10, v20
	v_xor_b32_e32 v20, 8, v249
	v_cmp_lt_i32_e32 vcc, v20, v12
	s_nop 1
	v_cndmask_b32_e32 v20, v249, v20, vcc
	v_lshlrev_b32_e32 v54, 2, v20
	s_nop 1
	v_mov_b32_dpp v20, v10 row_mirror row_mask:0xf bank_mask:0xf
	s_waitcnt lgkmcnt(0)
	v_add_f32_e32 v10, v10, v20
	v_xor_b32_e32 v20, 16, v249
	v_cmp_lt_i32_e32 vcc, v20, v12
	s_nop 1
	v_cndmask_b32_e32 v20, v249, v20, vcc
	v_lshlrev_b32_e32 v82, 2, v20
	v_mov_b32_e32 v20, v10
	v_mov_b32_e32 v107, v10
	s_nop 1
	v_permlane16_swap_b32_e32 v20, v107
	s_waitcnt lgkmcnt(0)
	s_nop 1
	v_add_f32_e32 v10, v20, v107
	v_xor_b32_e32 v20, 32, v249
	v_cmp_lt_i32_e32 vcc, v20, v12
	s_nop 1
	v_cndmask_b32_e32 v12, v249, v20, vcc
	v_lshlrev_b32_e32 v84, 2, v12
	v_mov_b32_e32 v12, v10
	v_mov_b32_e32 v107, v10
	s_nop 1
	v_permlane32_swap_b32_e32 v12, v107
	s_waitcnt lgkmcnt(0)
	s_nop 1
	v_add_f32_e32 v12, v12, v107
	v_fmac_f32_e32 v70, 0xba000000, v12
	v_fmac_f32_e32 v71, 0xba000000, v12
	v_fmac_f32_e32 v74, 0xba000000, v12
	v_fmac_f32_e32 v68, 0xba000000, v12
	v_fmac_f32_e32 v75, 0xba000000, v12
	v_fmac_f32_e32 v69, 0xba000000, v12
	v_mov_b32_e32 v67, v71
	v_mov_b32_e32 v79, v70
	v_pk_mul_f32 v[70:71], v[70:71], v[70:71]
	v_fmac_f32_e32 v64, 0xba000000, v12
	v_fmac_f32_e32 v65, 0xba000000, v12
	v_mov_b32_e32 v66, v69
	v_mov_b32_e32 v78, v68
	v_pk_fma_f32 v[68:69], v[68:69], v[68:69], v[70:71]
	v_mov_b32_e32 v71, v75
	v_mov_b32_e32 v81, v74
	v_pk_mul_f32 v[74:75], v[74:75], v[74:75]
	v_mov_b32_e32 v70, v65
	v_mov_b32_e32 v80, v64
	v_pk_fma_f32 v[64:65], v[64:65], v[64:65], v[74:75]
	v_fmac_f32_e32 v72, 0xba000000, v12
	v_fmac_f32_e32 v73, 0xba000000, v12
	v_fmac_f32_e32 v63, 0xba000000, v12
	v_pk_add_f32 v[64:65], v[68:69], v[64:65]
	v_fmac_f32_e32 v62, 0xba000000, v12
	v_mov_b32_e32 v68, v63
	v_mov_b32_e32 v69, v73
	v_mov_b32_e32 v63, v72
	v_pk_mul_f32 v[74:75], v[68:69], v[68:69]
	v_pk_mul_f32 v[72:73], v[62:63], v[62:63]
	v_fmac_f32_e32 v58, 0xba000000, v12
	v_pk_mov_b32 v[76:77], v[72:73], v[74:75] op_sel:[1,0]
	v_mov_b32_e32 v73, v75
	v_fmac_f32_e32 v59, 0xba000000, v12
	v_fmac_f32_e32 v60, 0xba000000, v12
	v_mul_f32_e32 v10, v58, v58
	v_pk_add_f32 v[72:73], v[76:77], v[72:73]
	v_fmac_f32_e32 v61, 0xba000000, v12
	v_pk_fma_f32 v[74:75], v[58:59], v[58:59], v[10:11] op_sel_hi:[1,1,0]
	v_mul_f32_e32 v10, v60, v60
	v_pk_add_f32 v[64:65], v[64:65], v[64:65] op_sel_hi:[0,1]
	v_pk_add_f32 v[72:73], v[72:73], v[72:73] op_sel_hi:[0,1]
	v_pk_fma_f32 v[76:77], v[60:61], v[60:61], v[10:11] op_sel_hi:[1,1,0]
	v_fmac_f32_e32 v53, 0xba000000, v12
	v_fmac_f32_e32 v55, 0xba000000, v12
	v_fmac_f32_e32 v49, 0xba000000, v12
	v_fmac_f32_e32 v51, 0xba000000, v12
	v_mul_f32_e32 v74, v51, v51
	v_mul_f32_e32 v76, v49, v49
	v_mul_f32_e32 v72, v55, v55
	v_mul_f32_e32 v64, v53, v53
	v_pk_add_f32 v[74:75], v[74:75], v[76:77]
	v_pk_add_f32 v[64:65], v[72:73], v[64:65]
	v_fmac_f32_e32 v4, 0xba000000, v12
	v_pk_add_f32 v[64:65], v[74:75], v[64:65]
	v_fmac_f32_e32 v5, 0xba000000, v12
	v_fmac_f32_e32 v57, 0xba000000, v12
	v_pk_add_f32 v[72:73], v[64:65], v[64:65] op_sel_hi:[0,1]
	v_fmac_f32_e32 v56, 0xba000000, v12
	v_mov_b32_e32 v64, v57
	v_mov_b32_e32 v65, v5
	v_mov_b32_e32 v57, v4
	v_pk_mul_f32 v[74:75], v[64:65], v[64:65]
	v_pk_mul_f32 v[4:5], v[56:57], v[56:57]
	v_fmac_f32_e32 v40, 0xba000000, v12
	v_pk_mov_b32 v[76:77], v[4:5], v[74:75] op_sel:[1,0]
	v_mov_b32_e32 v5, v75
	v_pk_add_f32 v[4:5], v[76:77], v[4:5]
	v_fmac_f32_e32 v41, 0xba000000, v12
	v_pk_add_f32 v[4:5], v[4:5], v[4:5] op_sel_hi:[0,1]
	v_fmac_f32_e32 v46, 0xba000000, v12
	v_mul_f32_e32 v4, v40, v40
	v_fmac_f32_e32 v47, 0xba000000, v12
	v_pk_fma_f32 v[74:75], v[40:41], v[40:41], v[4:5] op_sel_hi:[1,1,0]
	v_mul_f32_e32 v4, v46, v46
	v_pk_fma_f32 v[76:77], v[46:47], v[46:47], v[4:5] op_sel_hi:[1,1,0]
	v_fmac_f32_e32 v43, 0xba000000, v12
	v_fmac_f32_e32 v45, 0xba000000, v12
	v_fmac_f32_e32 v39, 0xba000000, v12
	v_fmac_f32_e32 v38, 0xba000000, v12
	v_mul_f32_e32 v74, v38, v38
	v_mul_f32_e32 v76, v39, v39
	v_mul_f32_e32 v4, v45, v45
	v_mul_f32_e32 v72, v43, v43
	v_pk_add_f32 v[74:75], v[74:75], v[76:77]
	v_pk_add_f32 v[4:5], v[4:5], v[72:73]
	v_lshlrev_b64 v[72:73], 2, v[2:3]
	v_pk_add_f32 v[4:5], v[74:75], v[4:5]
	v_lshl_add_u64 v[76:77], s[20:21], 0, v[72:73]
	v_add_f32_e32 v4, v4, v5
	s_nop 1
	v_mov_b32_dpp v5, v4 quad_perm:[1,0,3,2] row_mask:0xf bank_mask:0xf
	v_lshl_add_u64 v[74:75], s[18:19], 0, v[72:73]
	s_nop 1
	v_mov_b64_e32 v[86:87], v[212:213]
	v_mov_b64_e32 v[88:89], v[214:215]
	v_lshl_add_u64 v[72:73], s[22:23], 0, v[72:73]
	v_lshl_add_u64 v[72:73], v[72:73], 0, s[14:15]
	s_waitcnt lgkmcnt(0)
	v_add_f32_e32 v4, v4, v5
	s_nop 1
	v_mov_b32_dpp v5, v4 quad_perm:[2,3,0,1] row_mask:0xf bank_mask:0xf
	v_mov_b32_e32 v52, v55
	v_mov_b32_e32 v48, v51
	v_mov_b32_e32 v42, v45
	v_lshlrev_b32_e32 v45, 16, v37
	s_waitcnt lgkmcnt(0)
	v_add_f32_e32 v4, v4, v5
	s_nop 1
	v_mov_b32_dpp v5, v4 row_half_mirror row_mask:0xf bank_mask:0xf
	s_waitcnt lgkmcnt(0)
	v_add_f32_e32 v4, v4, v5
	s_nop 1
	v_mov_b32_dpp v5, v4 row_mirror row_mask:0xf bank_mask:0xf
	s_waitcnt lgkmcnt(0)
	v_add_f32_e32 v4, v4, v5
	v_mov_b32_e32 v5, v4
	v_mov_b32_e32 v107, v4
	s_nop 1
	v_permlane16_swap_b32_e32 v5, v107
	s_waitcnt lgkmcnt(0)
	s_nop 1
	v_add_f32_e32 v4, v5, v107
	v_mov_b32_e32 v5, v4
	v_mov_b32_e32 v107, v4
	s_nop 1
	v_permlane32_swap_b32_e32 v5, v107
	s_waitcnt lgkmcnt(0)
	s_nop 1
	v_add_f32_e32 v4, v5, v107
	v_fmamk_f32 v4, v4, 0x3a000000, v250
	v_cmp_gt_f32_e32 vcc, s96, v4
	v_mul_f32_e32 v5, 0x4f800000, v4
	s_nop 0
	v_cndmask_b32_e32 v4, v4, v5, vcc
	v_sqrt_f32_e32 v5, v4
	s_nop 0
	v_add_u32_e32 v10, -1, v5
	v_fma_f32 v12, -v10, v5, v4
	v_cmp_ge_f32_e64 s[10:11], 0, v12
	v_add_u32_e32 v12, 1, v5
	s_nop 0
	v_cndmask_b32_e64 v10, v5, v10, s[10:11]
	v_fma_f32 v5, -v12, v5, v4
	v_cmp_lt_f32_e64 s[10:11], 0, v5
	s_nop 1
	v_cndmask_b32_e64 v5, v10, v12, s[10:11]
	v_mul_f32_e32 v10, 0x37800000, v5
	v_cndmask_b32_e32 v5, v5, v10, vcc
	v_cmp_class_f32_e32 vcc, v4, v251
	s_nop 1
	v_cndmask_b32_e32 v4, v5, v4, vcc
	v_div_scale_f32 v5, s[10:11], v4, v4, 1.0
	v_rcp_f32_e32 v10, v5
	s_lshl_b64 s[10:11], s[24:25], 13
	s_add_u32 s22, s22, s10
	s_addc_u32 s23, s23, s11
	v_fma_f32 v12, -v5, v10, 1.0
	v_fmac_f32_e32 v10, v12, v10
	v_div_scale_f32 v12, vcc, 1.0, v4, 1.0
	v_mul_f32_e32 v20, v12, v10
	v_fma_f32 v22, -v5, v20, v12
	v_fmac_f32_e32 v20, v22, v10
	v_fma_f32 v5, -v5, v20, v12
	v_div_fmas_f32 v5, v5, v10, v20
	v_div_fixup_f32 v10, v5, v4, 1.0
	s_nop 1
	v_mov_b64_e32 v[2:3], v[180:181]
	v_mov_b64_e32 v[4:5], v[182:183]
	v_pk_mul_f32 v[78:79], v[78:79], v[10:11] op_sel_hi:[1,0]
	v_pk_mul_f32 v[80:81], v[80:81], v[10:11] op_sel_hi:[1,0]
	v_pk_mul_f32 v[70:71], v[70:71], v[10:11] op_sel_hi:[1,0]
	v_pk_mul_f32 v[66:67], v[66:67], v[10:11] op_sel_hi:[1,0]
	v_pk_mul_f32 v[62:63], v[62:63], v[10:11] op_sel_hi:[1,0]
	v_pk_mul_f32 v[60:61], v[60:61], v[10:11] op_sel_hi:[1,0]
	v_pk_mul_f32 v[58:59], v[58:59], v[10:11] op_sel_hi:[1,0]
	v_pk_mul_f32 v[52:53], v[52:53], v[10:11] op_sel_hi:[1,0]
	v_pk_mul_f32 v[48:49], v[48:49], v[10:11] op_sel_hi:[1,0]
	v_pk_mul_f32 v[46:47], v[46:47], v[10:11] op_sel_hi:[1,0]
	v_pk_mul_f32 v[40:41], v[40:41], v[10:11] op_sel_hi:[1,0]
	v_pk_mul_f32 v[38:39], v[38:39], v[10:11] op_sel_hi:[1,0]
	v_add_f32_e32 v22, v28, v29
	v_add_f32_e32 v12, v14, v15
	s_add_i32 s8, s8, s26
	s_add_u32 s16, s16, s34
	s_addc_u32 s17, s17, s35
	s_add_u32 s14, s14, s36
	s_addc_u32 s15, s15, s37
	s_cmpk_lt_i32 s8, 0x2000
	s_nop 0
	v_pk_fma_f32 v[2:3], v[2:3], v[78:79], v[86:87]
	v_add_co_u32_e32 v78, vcc, s38, v72
	v_pk_fma_f32 v[4:5], v[4:5], v[80:81], v[88:89]
	s_nop 0
	v_addc_co_u32_e32 v79, vcc, -1, v73, vcc
	global_store_dwordx4 v[78:79], v[2:5], off offset:-3072
	s_nop 1
	v_mov_b64_e32 v[2:3], v[184:185]
	v_mov_b64_e32 v[4:5], v[186:187]
	s_nop 0
	s_nop 1
	v_mov_b64_e32 v[86:87], v[216:217]
	v_mov_b64_e32 v[88:89], v[218:219]
	s_nop 0
	v_pk_fma_f32 v[2:3], v[2:3], v[66:67], v[86:87]
	v_pk_fma_f32 v[4:5], v[4:5], v[70:71], v[88:89]
	global_store_dwordx4 v[78:79], v[2:5], off offset:-2048
	s_nop 1
	v_mov_b64_e32 v[2:3], v[188:189]
	v_mov_b64_e32 v[4:5], v[190:191]
	s_nop 1
	v_mov_b64_e32 v[86:87], v[220:221]
	v_mov_b64_e32 v[88:89], v[222:223]
	v_pk_mul_f32 v[66:67], v[68:69], v[10:11] op_sel_hi:[1,0]
	s_nop 0
	v_pk_fma_f32 v[2:3], v[2:3], v[62:63], v[86:87]
	v_pk_fma_f32 v[4:5], v[4:5], v[66:67], v[88:89]
	global_store_dwordx4 v[78:79], v[2:5], off offset:-1024
	s_nop 1
	v_mov_b64_e32 v[2:3], v[192:193]
	v_mov_b64_e32 v[4:5], v[194:195]
	s_nop 0
	s_nop 1
	v_mov_b64_e32 v[66:67], v[236:237]
	v_mov_b64_e32 v[68:69], v[238:239]
	v_add_co_u32_e32 v62, vcc, s82, v76
	s_nop 0
	v_pk_fma_f32 v[2:3], v[2:3], v[58:59], v[66:67]
	v_pk_fma_f32 v[4:5], v[4:5], v[60:61], v[68:69]
	v_addc_co_u32_e32 v63, vcc, 0, v77, vcc
	global_store_dwordx4 v[72:73], v[2:5], off offset:-4096
	v_add_co_u32_e32 v66, vcc, s82, v74
	s_nop 1
	v_mov_b64_e32 v[2:3], v[196:197]
	v_mov_b64_e32 v[4:5], v[198:199]
	s_nop 0
	v_addc_co_u32_e32 v67, vcc, 0, v75, vcc
	s_nop 1
	v_mov_b64_e32 v[58:59], v[240:241]
	v_mov_b64_e32 v[60:61], v[242:243]
	s_nop 0
	v_pk_fma_f32 v[2:3], v[2:3], v[48:49], v[58:59]
	v_pk_fma_f32 v[4:5], v[4:5], v[52:53], v[60:61]
	global_store_dwordx4 v[72:73], v[2:5], off offset:-3072
	s_nop 1
	v_mov_b64_e32 v[2:3], v[200:201]
	v_mov_b64_e32 v[4:5], v[202:203]
	s_nop 0
	s_nop 1
	v_mov_b64_e32 v[58:59], v[128:129]
	v_mov_b64_e32 v[60:61], v[130:131]
	v_pk_mul_f32 v[48:49], v[64:65], v[10:11] op_sel_hi:[1,0]
	v_pk_mul_f32 v[52:53], v[56:57], v[10:11] op_sel_hi:[1,0]
	s_nop 0
	v_pk_fma_f32 v[4:5], v[4:5], v[48:49], v[60:61]
	v_pk_fma_f32 v[2:3], v[2:3], v[52:53], v[58:59]
	global_store_dwordx4 v[72:73], v[2:5], off offset:-2048
	s_nop 1
	v_mov_b64_e32 v[2:3], v[204:205]
	v_mov_b64_e32 v[4:5], v[206:207]
	s_nop 1
	v_mov_b64_e32 v[56:57], v[132:133]
	v_mov_b64_e32 v[58:59], v[134:135]
	s_nop 0
	v_pk_fma_f32 v[2:3], v[2:3], v[40:41], v[56:57]
	v_pk_fma_f32 v[4:5], v[4:5], v[46:47], v[58:59]
	global_store_dwordx4 v[72:73], v[2:5], off offset:-1024
	s_nop 1
	v_mov_b64_e32 v[2:3], v[208:209]
	v_mov_b64_e32 v[4:5], v[210:211]
	s_nop 0
	s_nop 1
	v_mov_b64_e32 v[46:47], v[140:141]
	v_mov_b64_e32 v[48:49], v[142:143]
	v_pk_mul_f32 v[40:41], v[42:43], v[10:11] op_sel_hi:[1,0]
	v_and_b32_e32 v43, 0xffff0000, v31
	v_and_b32_e32 v42, 0xffff0000, v30
	v_add_f32_e32 v10, v16, v17
	s_nop 0
	v_pk_fma_f32 v[2:3], v[38:39], v[2:3], v[46:47]
	v_pk_fma_f32 v[4:5], v[40:41], v[4:5], v[48:49]
	v_lshlrev_b32_e32 v38, 16, v34
	v_lshlrev_b32_e32 v39, 16, v36
	v_and_b32_e32 v47, 0xffff0000, v36
	v_and_b32_e32 v46, 0xffff0000, v34
	v_and_b32_e32 v49, 0xffff0000, v37
	v_and_b32_e32 v48, 0xffff0000, v35
	global_store_dwordx4 v[72:73], v[2:5], off
	v_and_b32_e32 v41, 0xffff0000, v33
	v_and_b32_e32 v40, 0xffff0000, v32
	v_pk_add_f32 v[2:3], v[38:39], v[46:47]
	v_pk_add_f32 v[4:5], v[44:45], v[48:49]
	s_nop 0
	v_pk_add_f32 v[2:3], v[2:3], v[4:5]
	v_lshlrev_b32_e32 v5, 16, v33
	v_add_f32_e32 v2, 0, v2
	v_lshlrev_b32_e32 v4, 16, v32
	v_add_f32_e32 v20, v2, v3
	v_pk_add_f32 v[2:3], v[4:5], v[40:41]
	v_pk_add_f32 v[32:33], v[24:25], v[22:23]
	v_pk_add_f32 v[2:3], v[2:3], v[2:3] op_sel:[0,1] op_sel_hi:[1,0]
	s_nop 0
	v_mov_b32_e32 v3, v19
	v_pk_add_f32 v[2:3], v[20:21], v[2:3]
	s_nop 0
	v_pk_add_f32 v[32:33], v[2:3], v[32:33]
	v_lshlrev_b32_e32 v3, 16, v31
	v_lshlrev_b32_e32 v2, 16, v30
	v_pk_add_f32 v[30:31], v[2:3], v[42:43]
	v_pk_add_f32 v[32:33], v[32:33], v[32:33] op_sel:[0,1] op_sel_hi:[1,0]
	v_pk_add_f32 v[30:31], v[30:31], v[30:31] op_sel:[0,1] op_sel_hi:[1,0]
	v_mov_b32_e32 v33, v8
	v_mov_b32_e32 v31, v9
	v_pk_add_f32 v[30:31], v[32:33], v[30:31]
	v_pk_add_f32 v[32:33], v[12:13], v[10:11]
	s_nop 0
	v_pk_add_f32 v[30:31], v[30:31], v[32:33]
	s_nop 0
	v_add_f32_e32 v10, v30, v31
	s_nop 1
	v_mov_b32_dpp v12, v10 quad_perm:[1,0,3,2] row_mask:0xf bank_mask:0xf
	s_waitcnt lgkmcnt(0)
	v_add_f32_e32 v10, v10, v12
	s_nop 1
	v_mov_b32_dpp v12, v10 quad_perm:[2,3,0,1] row_mask:0xf bank_mask:0xf
	s_waitcnt lgkmcnt(0)
	v_add_f32_e32 v10, v10, v12
	s_nop 1
	v_mov_b32_dpp v12, v10 row_half_mirror row_mask:0xf bank_mask:0xf
	s_waitcnt lgkmcnt(0)
	v_add_f32_e32 v10, v10, v12
	s_nop 1
	v_mov_b32_dpp v12, v10 row_mirror row_mask:0xf bank_mask:0xf
	s_waitcnt lgkmcnt(0)
	v_add_f32_e32 v10, v10, v12
	v_mov_b32_e32 v12, v10
	v_mov_b32_e32 v107, v10
	s_nop 1
	v_permlane16_swap_b32_e32 v12, v107
	s_waitcnt lgkmcnt(0)
	s_nop 1
	v_add_f32_e32 v10, v12, v107
	v_mov_b32_e32 v12, v10
	v_mov_b32_e32 v107, v10
	s_nop 1
	v_permlane32_swap_b32_e32 v12, v107
	s_waitcnt lgkmcnt(0)
	s_nop 1
	v_add_f32_e32 v12, v12, v107
	v_fmac_f32_e32 v48, 0xba000000, v12
	v_fmac_f32_e32 v46, 0xba000000, v12
	v_fmac_f32_e32 v49, 0xba000000, v12
	v_fmac_f32_e32 v47, 0xba000000, v12
	v_fmac_f32_e32 v44, 0xba000000, v12
	v_fmac_f32_e32 v38, 0xba000000, v12
	v_fmac_f32_e32 v45, 0xba000000, v12
	v_fmac_f32_e32 v39, 0xba000000, v12
	v_mov_b32_e32 v31, v47
	v_mov_b32_e32 v35, v46
	v_pk_mul_f32 v[32:33], v[46:47], v[46:47]
	v_pk_mul_f32 v[46:47], v[48:49], v[48:49]
	v_mov_b32_e32 v30, v39
	v_mov_b32_e32 v34, v38
	v_pk_fma_f32 v[38:39], v[38:39], v[38:39], v[32:33]
	v_mov_b32_e32 v32, v45
	v_mov_b32_e32 v36, v44
	v_pk_fma_f32 v[44:45], v[44:45], v[44:45], v[46:47]
	v_fmac_f32_e32 v40, 0xba000000, v12
	v_pk_add_f32 v[38:39], v[38:39], v[44:45]
	v_fmac_f32_e32 v41, 0xba000000, v12
	v_fmac_f32_e32 v5, 0xba000000, v12
	v_pk_add_f32 v[44:45], v[38:39], v[38:39] op_sel_hi:[0,1]
	v_fmac_f32_e32 v4, 0xba000000, v12
	v_mov_b32_e32 v38, v5
	v_mov_b32_e32 v39, v41
	v_mov_b32_e32 v5, v40
	v_pk_mul_f32 v[46:47], v[38:39], v[38:39]
	v_pk_mul_f32 v[40:41], v[4:5], v[4:5]
	v_fmac_f32_e32 v26, 0xba000000, v12
	v_mov_b32_e32 v33, v49
	v_mov_b32_e32 v37, v48
	v_pk_mov_b32 v[48:49], v[40:41], v[46:47] op_sel:[1,0]
	v_mov_b32_e32 v41, v47
	v_fmac_f32_e32 v27, 0xba000000, v12
	v_fmac_f32_e32 v28, 0xba000000, v12
	v_mul_f32_e32 v10, v26, v26
	v_pk_add_f32 v[40:41], v[48:49], v[40:41]
	v_fmac_f32_e32 v29, 0xba000000, v12
	v_pk_fma_f32 v[46:47], v[26:27], v[26:27], v[10:11] op_sel_hi:[1,1,0]
	v_mul_f32_e32 v10, v28, v28
	v_pk_add_f32 v[40:41], v[40:41], v[40:41] op_sel_hi:[0,1]
	v_pk_fma_f32 v[48:49], v[28:29], v[28:29], v[10:11] op_sel_hi:[1,1,0]
	v_fmac_f32_e32 v23, 0xba000000, v12
	v_fmac_f32_e32 v25, 0xba000000, v12
	v_fmac_f32_e32 v19, 0xba000000, v12
	v_fmac_f32_e32 v21, 0xba000000, v12
	v_mul_f32_e32 v46, v21, v21
	v_mul_f32_e32 v48, v19, v19
	v_mul_f32_e32 v40, v25, v25
	v_mul_f32_e32 v44, v23, v23
	v_pk_add_f32 v[46:47], v[46:47], v[48:49]
	v_pk_add_f32 v[40:41], v[40:41], v[44:45]
	v_fmac_f32_e32 v42, 0xba000000, v12
	v_pk_add_f32 v[40:41], v[46:47], v[40:41]
	v_fmac_f32_e32 v43, 0xba000000, v12
	v_fmac_f32_e32 v3, 0xba000000, v12
	v_pk_add_f32 v[44:45], v[40:41], v[40:41] op_sel_hi:[0,1]
	v_fmac_f32_e32 v2, 0xba000000, v12
	v_mov_b32_e32 v40, v3
	v_mov_b32_e32 v41, v43
	v_mov_b32_e32 v3, v42
	v_pk_mul_f32 v[46:47], v[40:41], v[40:41]
	v_pk_mul_f32 v[42:43], v[2:3], v[2:3]
	v_fmac_f32_e32 v14, 0xba000000, v12
	v_pk_mov_b32 v[48:49], v[42:43], v[46:47] op_sel:[1,0]
	v_mov_b32_e32 v43, v47
	v_fmac_f32_e32 v15, 0xba000000, v12
	v_fmac_f32_e32 v16, 0xba000000, v12
	v_mul_f32_e32 v10, v14, v14
	v_pk_add_f32 v[42:43], v[48:49], v[42:43]
	v_fmac_f32_e32 v17, 0xba000000, v12
	v_pk_fma_f32 v[46:47], v[14:15], v[14:15], v[10:11] op_sel_hi:[1,1,0]
	v_mul_f32_e32 v10, v16, v16
	v_pk_add_f32 v[42:43], v[42:43], v[42:43] op_sel_hi:[0,1]
	v_pk_fma_f32 v[48:49], v[16:17], v[16:17], v[10:11] op_sel_hi:[1,1,0]
	v_fmac_f32_e32 v11, 0xba000000, v12
	v_fmac_f32_e32 v13, 0xba000000, v12
	v_fmac_f32_e32 v9, 0xba000000, v12
	v_fmac_f32_e32 v8, 0xba000000, v12
	v_mul_f32_e32 v46, v8, v8
	v_mul_f32_e32 v48, v9, v9
	v_mul_f32_e32 v42, v13, v13
	v_mul_f32_e32 v44, v11, v11
	v_pk_add_f32 v[46:47], v[46:47], v[48:49]
	v_pk_add_f32 v[42:43], v[42:43], v[44:45]
	s_nop 0
	v_pk_add_f32 v[42:43], v[46:47], v[42:43]
	s_nop 0
	v_add_f32_e32 v10, v42, v43
	s_nop 1
	v_mov_b32_dpp v7, v10 quad_perm:[1,0,3,2] row_mask:0xf bank_mask:0xf
	v_lshlrev_b32_e32 v42, 2, v1
	v_ashrrev_i32_e32 v43, 31, v42
	s_waitcnt lgkmcnt(0)
	v_add_f32_e32 v7, v10, v7
	s_nop 1
	v_mov_b32_dpp v10, v7 quad_perm:[2,3,0,1] row_mask:0xf bank_mask:0xf
	s_waitcnt lgkmcnt(0)
	v_add_f32_e32 v7, v7, v10
	s_nop 1
	v_mov_b32_dpp v10, v7 row_half_mirror row_mask:0xf bank_mask:0xf
	s_waitcnt lgkmcnt(0)
	v_add_f32_e32 v7, v7, v10
	s_nop 1
	v_mov_b32_dpp v10, v7 row_mirror row_mask:0xf bank_mask:0xf
	v_lshlrev_b64 v[54:55], 2, v[42:43]
	v_lshl_add_u64 v[44:45], s[20:21], 0, v[54:55]
	v_lshl_add_u64 v[42:43], s[18:19], 0, v[54:55]
	s_nop 1
	v_mov_b64_e32 v[46:47], v[180:181]
	v_mov_b64_e32 v[48:49], v[182:183]
	s_nop 1
	v_mov_b64_e32 v[50:51], v[212:213]
	v_mov_b64_e32 v[52:53], v[214:215]
	s_waitcnt lgkmcnt(0)
	v_add_f32_e32 v7, v7, v10
	v_mov_b32_e32 v10, v7
	v_mov_b32_e32 v107, v7
	s_nop 1
	v_permlane16_swap_b32_e32 v10, v107
	s_waitcnt lgkmcnt(0)
	s_nop 1
	v_add_f32_e32 v7, v10, v107
	v_mov_b32_e32 v10, v7
	v_mov_b32_e32 v107, v7
	s_nop 1
	v_permlane32_swap_b32_e32 v10, v107
	s_waitcnt lgkmcnt(0)
	s_nop 1
	v_add_f32_e32 v7, v10, v107
	v_fmamk_f32 v7, v7, 0x3a000000, v250
	v_cmp_gt_f32_e32 vcc, s96, v7
	v_mul_f32_e32 v10, 0x4f800000, v7
	s_nop 0
	v_cndmask_b32_e32 v7, v7, v10, vcc
	v_sqrt_f32_e32 v10, v7
	s_nop 0
	v_add_u32_e32 v12, -1, v10
	v_fma_f32 v18, -v12, v10, v7
	v_cmp_ge_f32_e64 s[10:11], 0, v18
	v_add_u32_e32 v18, 1, v10
	s_nop 0
	v_cndmask_b32_e64 v12, v10, v12, s[10:11]
	v_fma_f32 v10, -v18, v10, v7
	v_cmp_lt_f32_e64 s[10:11], 0, v10
	s_nop 1
	v_cndmask_b32_e64 v10, v12, v18, s[10:11]
	v_mul_f32_e32 v12, 0x37800000, v10
	v_cndmask_b32_e32 v10, v10, v12, vcc
	v_cmp_class_f32_e32 vcc, v7, v251
	s_nop 1
	v_cndmask_b32_e32 v7, v10, v7, vcc
	v_div_scale_f32 v10, s[10:11], v7, v7, 1.0
	v_rcp_f32_e32 v12, v10
	s_nop 0
	v_fma_f32 v18, -v10, v12, 1.0
	v_fmac_f32_e32 v12, v18, v12
	v_div_scale_f32 v18, vcc, 1.0, v7, 1.0
	v_mul_f32_e32 v20, v18, v12
	v_fma_f32 v22, -v10, v20, v18
	v_fmac_f32_e32 v20, v22, v12
	v_fma_f32 v10, -v10, v20, v18
	v_div_fmas_f32 v10, v10, v12, v20
	v_div_fixup_f32 v12, v10, v7, 1.0
	v_pk_mul_f32 v[36:37], v[36:37], v[12:13] op_sel_hi:[1,0]
	v_pk_mul_f32 v[34:35], v[34:35], v[12:13] op_sel_hi:[1,0]
	v_pk_mul_f32 v[32:33], v[32:33], v[12:13] op_sel_hi:[1,0]
	v_pk_mul_f32 v[30:31], v[30:31], v[12:13] op_sel_hi:[1,0]
	v_pk_mul_f32 v[38:39], v[38:39], v[12:13] op_sel_hi:[1,0]
	v_pk_mul_f32 v[4:5], v[4:5], v[12:13] op_sel_hi:[1,0]
	v_pk_mul_f32 v[26:27], v[26:27], v[12:13] op_sel_hi:[1,0]
	v_mov_b32_e32 v18, v21
	v_mov_b32_e32 v22, v25
	v_pk_mul_f32 v[18:19], v[18:19], v[12:13] op_sel_hi:[1,0]
	v_pk_mul_f32 v[2:3], v[2:3], v[12:13] op_sel_hi:[1,0]
	v_pk_mul_f32 v[16:17], v[16:17], v[12:13] op_sel_hi:[1,0]
	v_pk_mul_f32 v[14:15], v[14:15], v[12:13] op_sel_hi:[1,0]
	v_mov_b32_e32 v10, v13
	v_pk_mul_f32 v[10:11], v[10:11], v[12:13] op_sel_hi:[1,0]
	v_pk_mul_f32 v[8:9], v[8:9], v[12:13] op_sel_hi:[1,0]
	s_nop 0
	v_pk_fma_f32 v[34:35], v[46:47], v[34:35], v[50:51]
	v_pk_fma_f32 v[36:37], v[48:49], v[36:37], v[52:53]
	v_lshl_add_u64 v[50:51], s[22:23], 0, v[54:55]
	global_store_dwordx4 v[50:51], v[34:37], off
	s_nop 1
	v_mov_b64_e32 v[34:35], v[184:185]
	v_mov_b64_e32 v[36:37], v[186:187]
	s_nop 0
	s_nop 1
	v_mov_b64_e32 v[46:47], v[216:217]
	v_mov_b64_e32 v[48:49], v[218:219]
	s_nop 0
	v_pk_fma_f32 v[30:31], v[34:35], v[30:31], v[46:47]
	v_pk_fma_f32 v[32:33], v[36:37], v[32:33], v[48:49]
	global_store_dwordx4 v[50:51], v[30:33], off offset:1024
	s_nop 1
	v_mov_b64_e32 v[30:31], v[188:189]
	v_mov_b64_e32 v[32:33], v[190:191]
	s_nop 1
	v_mov_b64_e32 v[34:35], v[220:221]
	v_mov_b64_e32 v[36:37], v[222:223]
	s_nop 0
	v_pk_fma_f32 v[30:31], v[30:31], v[4:5], v[34:35]
	v_pk_fma_f32 v[32:33], v[32:33], v[38:39], v[36:37]
	global_store_dwordx4 v[50:51], v[30:33], off offset:2048
	s_nop 1
	v_mov_b64_e32 v[30:31], v[192:193]
	v_mov_b64_e32 v[32:33], v[194:195]
	s_nop 0
	s_nop 1
	v_mov_b64_e32 v[34:35], v[236:237]
	v_mov_b64_e32 v[36:37], v[238:239]
	v_pk_mul_f32 v[4:5], v[28:29], v[12:13] op_sel_hi:[1,0]
	s_nop 0
	v_pk_fma_f32 v[26:27], v[30:31], v[26:27], v[34:35]
	v_add_co_u32_e32 v34, vcc, s82, v44
	v_pk_fma_f32 v[28:29], v[32:33], v[4:5], v[36:37]
	s_nop 0
	v_addc_co_u32_e32 v35, vcc, 0, v45, vcc
	global_store_dwordx4 v[50:51], v[26:29], off offset:3072
	v_add_co_u32_e32 v36, vcc, s82, v42
	s_nop 1
	v_mov_b64_e32 v[26:27], v[196:197]
	v_mov_b64_e32 v[28:29], v[198:199]
	s_nop 0
	v_addc_co_u32_e32 v37, vcc, 0, v43, vcc
	s_nop 1
	v_mov_b64_e32 v[30:31], v[240:241]
	v_mov_b64_e32 v[32:33], v[242:243]
	v_pk_mul_f32 v[4:5], v[22:23], v[12:13] op_sel_hi:[1,0]
	s_nop 0
	v_pk_fma_f32 v[18:19], v[26:27], v[18:19], v[30:31]
	v_add_co_u32_e32 v26, vcc, s82, v50
	v_pk_fma_f32 v[20:21], v[28:29], v[4:5], v[32:33]
	s_nop 0
	v_addc_co_u32_e32 v27, vcc, 0, v51, vcc
	global_store_dwordx4 v[26:27], v[18:21], off
	s_nop 1
	v_mov_b64_e32 v[18:19], v[200:201]
	v_mov_b64_e32 v[20:21], v[202:203]
	s_nop 0
	s_nop 1
	v_mov_b64_e32 v[22:23], v[128:129]
	v_mov_b64_e32 v[24:25], v[130:131]
	v_pk_mul_f32 v[4:5], v[40:41], v[12:13] op_sel_hi:[1,0]
	s_nop 0
	v_pk_fma_f32 v[2:3], v[18:19], v[2:3], v[22:23]
	v_pk_fma_f32 v[4:5], v[20:21], v[4:5], v[24:25]
	global_store_dwordx4 v[26:27], v[2:5], off offset:1024
	s_nop 1
	v_mov_b64_e32 v[2:3], v[204:205]
	v_mov_b64_e32 v[4:5], v[206:207]
	s_nop 1
	v_mov_b64_e32 v[18:19], v[132:133]
	v_mov_b64_e32 v[20:21], v[134:135]
	s_nop 0
	v_pk_fma_f32 v[2:3], v[2:3], v[14:15], v[18:19]
	v_pk_fma_f32 v[4:5], v[4:5], v[16:17], v[20:21]
	global_store_dwordx4 v[26:27], v[2:5], off offset:2048
	s_nop 1
	v_mov_b64_e32 v[2:3], v[208:209]
	v_mov_b64_e32 v[4:5], v[210:211]
	s_nop 0
	s_nop 1
	v_mov_b64_e32 v[14:15], v[140:141]
	v_mov_b64_e32 v[16:17], v[142:143]
	s_nop 0
	v_pk_fma_f32 v[2:3], v[8:9], v[2:3], v[14:15]
	v_pk_fma_f32 v[4:5], v[10:11], v[4:5], v[16:17]
	global_store_dwordx4 v[26:27], v[2:5], off offset:3072
	s_cbranch_scc1 .LBB0_1705
